# v15_ml4
# speedup vs baseline: 1.0130x; 1.0130x over previous
; #define STAGE(PP, RSRC, br, kt) do { const int _so = ((br) * K + (kt) * BK) * 2; \
;       __builtin_amdgcn_raw_ptr_buffer_load_lds(RSRC, LDSP((char*)(PP) + ldsoff), 16, voff0, _so, 0, 0); \
;       __builtin_amdgcn_raw_ptr_buffer_load_lds(RSRC, LDSP((char*)(PP) + ldsoff + 8192), 16, voff1, _so, 0, 0); \
;     } while (0)
; #define LDB(dst, b, h) for (int n = 0; n < 2; ++n) for (int k = 0; k < 2; ++k) \
;     dst[n][k] = *reinterpret_cast<const bf16x8*>((char*)SB(b, h) + lds_byte(wc * 32 + n * 16 + fr, k * 32 + fq * 8))
; #define WAIT_V(n) asm volatile("s_waitcnt vmcnt(" #n ")" ::: "memory")
; #define BAR __builtin_amdgcn_s_barrier()
; __device__ __forceinline__ void gemm_tile(const Params& P, const GArgs& ga, const TileDesc& td, int wid_s) {
;     ...
;   STAGE(SB(0, 0), Bt, bcol, 0); STAGE(SA(0, 0), A, brow, 0);
;   STAGE(SB(0, 1), Bt, bcol + HALF, 0); STAGE(SA(0, 1), A, brow + HALF, 0);
;   if (wr == 1) BAR;
;   WAIT_V(4); BAR;
;   STAGE(SB(1, 0), Bt, bcol, 1); STAGE(SA(1, 0), A, brow, 1); STAGE(SB(1, 1), Bt, bcol + HALF, 1);
;   WAIT_V(6); BAR;
;   LDB(B0, 0, 0);
;   for (int t = 0; t < nt - 2; t += 2) {
.LBB0_304:
	s_or_b64 exec, exec, s[0:1]
	s_mov_b32 m0, s75
	s_bitset1_b32 s99, 7
	s_mov_b32 s6, s10
	s_mov_b32 s7, s11
	s_waitcnt vmcnt(4)
	s_barrier
	buffer_load_dwordx4 v148, s[4:7], s99 offen lds
	s_mov_b32 m0, s74
	s_bitset1_b32 s98, 7
	buffer_load_dwordx4 v149, s[4:7], s99 offen lds
	s_mov_b32 m0, s83
	s_bitset1_b32 s38, 7
	buffer_load_dwordx4 v148, s[8:11], s98 offen lds
	s_mov_b32 m0, s82
	v_and_b32_e32 v19, 15, v0
	buffer_load_dwordx4 v149, s[8:11], s98 offen lds
	s_mov_b32 m0, s69
	v_lshlrev_b32_e32 v3, 2, v0
	buffer_load_dwordx4 v148, s[4:7], s38 offen lds
	s_mov_b32 m0, s68
	v_and_b32_e32 v18, 48, v0
	buffer_load_dwordx4 v149, s[4:7], s38 offen lds
	v_lshlrev_b32_e32 v2, 6, v19
	v_and_b32_e32 v3, 32, v3
	v_bitop3_b32 v146, v2, v3, v18 bitop3:0x36
	s_add_i32 s0, 0, 0x10000
	v_lshlrev_b32_e32 v3, 6, v0
	v_add_u32_e32 v2, s0, v146
	v_and_b32_e32 v147, 0x3000, v3
	v_add_u32_e32 v162, v2, v147
	s_waitcnt vmcnt(6)
	s_barrier
	ds_read_b128 v[2:5], v162
	ds_read_b128 v[6:9], v162 offset:1024
	s_waitcnt vmcnt(16)
	ds_read_b128 v[10:13], v162 offset:2048
	ds_read_b128 v[14:17], v162 offset:3072
	s_waitcnt lgkmcnt(0)
	s_barrier
	s_barrier
	v_lshlrev_b32_e32 v20, 6, v24
	v_or_b32_e32 v21, v20, v19
	v_or_b32_e32 v27, 16, v20
	v_or_b32_e32 v26, 32, v20
	v_or_b32_e32 v25, 48, v20
	s_cmp_gt_u32 s17, 2
	s_mov_b64 s[0:1], -1
	v_lshlrev_b32_e32 v159, 13, v24
	v_lshlrev_b32_e32 v22, 6, v21
	v_lshlrev_b32_e32 v23, 2, v21
	v_or_b32_e32 v21, v27, v19
	v_lshlrev_b32_e32 v161, 7, v27
	v_or_b32_e32 v20, v26, v19
	v_lshlrev_b32_e32 v160, 7, v26
	v_or_b32_e32 v19, v25, v19
	v_lshlrev_b32_e32 v158, 7, v25
	s_cbranch_scc1 .LBB0_306
	v_lshlrev_b32_e32 v163, 13, v24
	v_and_b32_e32 v24, 0x3c0, v22
	s_waitcnt vmcnt(15)
	v_and_b32_e32 v28, 32, v23
	v_bitop3_b32 v150, v24, v28, v18 bitop3:0x36
	v_lshlrev_b32_e32 v24, 6, v21
	v_lshlrev_b32_e32 v28, 2, v21
	v_and_b32_e32 v24, 0x3c0, v24
	v_and_b32_e32 v28, 32, v28
	v_bitop3_b32 v152, v24, v28, v18 bitop3:0x36
	v_lshlrev_b32_e32 v164, 7, v27
	v_lshlrev_b32_e32 v24, 6, v20
	v_lshlrev_b32_e32 v27, 2, v20
	v_and_b32_e32 v24, 0x3c0, v24
	v_and_b32_e32 v27, 32, v27
	v_bitop3_b32 v154, v24, v27, v18 bitop3:0x36
	v_lshlrev_b32_e32 v165, 7, v26
	v_lshlrev_b32_e32 v24, 6, v19
	v_lshlrev_b32_e32 v26, 2, v19
	v_and_b32_e32 v24, 0x3c0, v24
	v_and_b32_e32 v26, 32, v26
	v_lshlrev_b32_e32 v166, 7, v25
	v_or_b32_e32 v151, 0x400, v163
	v_or_b32_e32 v153, 0x400, v164
	v_or_b32_e32 v155, 0x400, v165
	v_bitop3_b32 v156, v24, v26, v18 bitop3:0x36
	v_or_b32_e32 v157, 0x400, v166
	s_mov_b64 s[0:1], 0

; #define STAGE(PP, RSRC, br, kt) do { const int _so = ((br) * K + (kt) * BK) * 2; \
;       __builtin_amdgcn_raw_ptr_buffer_load_lds(RSRC, LDSP((char*)(PP) + ldsoff), 16, voff0, _so, 0, 0); \
;       __builtin_amdgcn_raw_ptr_buffer_load_lds(RSRC, LDSP((char*)(PP) + ldsoff + 8192), 16, voff1, _so, 0, 0); \
;     } while (0)
; #define LDA(dst, b, h) for (int m = 0; m < 4; ++m) for (int k = 0; k < 2; ++k) \
;     dst[m][k] = *reinterpret_cast<const bf16x8*>((char*)SA(b, h) + lds_byte(wr * 64 + m * 16 + fr, k * 32 + fq * 8))
; #define LDB(dst, b, h) for (int n = 0; n < 2; ++n) for (int k = 0; k < 2; ++k) \
;     dst[n][k] = *reinterpret_cast<const bf16x8*>((char*)SB(b, h) + lds_byte(wc * 32 + n * 16 + fr, k * 32 + fq * 8))
; #define MMA(ai, bj, At_, Bt_) do { __builtin_amdgcn_s_setprio(1); \
;     for (int m = 0; m < 4; ++m) for (int n = 0; n < 2; ++n) for (int k = 0; k < 2; ++k) \
;       acc[ai][bj][m][n] = __builtin_amdgcn_mfma_f32_16x16x32_bf16(At_[m][k], Bt_[n][k], acc[ai][bj][m][n], 0, 0, 0); \
;     __builtin_amdgcn_s_setprio(0); } while (0)
; #define WAIT_V(n) asm volatile("s_waitcnt vmcnt(" #n ")" ::: "memory")
; #define WAIT_L(n) asm volatile("s_waitcnt lgkmcnt(" #n ")" ::: "memory")
; #define BAR __builtin_amdgcn_s_barrier()
; #define SCHED __builtin_amdgcn_sched_barrier(0)
; __device__ __forceinline__ void gemm_tile(const Params& P, const GArgs& ga, const TileDesc& td, int wid_s) {
;     ...
;   for (int t = 0; t < nt - 2; t += 2) {
;     LDA(At, 0, 0); STAGE(SA(1, 1), A, brow + HALF, t + 1);
;     WAIT_L(8); BAR; WAIT_L(0); MMA(0, 0, At, B0); BAR; SCHED;
;     LDB(B1, 0, 1); STAGE(SB(0, 0), Bt, bcol, t + 2);
;     BAR; WAIT_L(0); MMA(0, 1, At, B1); BAR;
;     LDA(At, 0, 1); STAGE(SA(0, 0), A, brow, t + 2);
;     WAIT_V(4); BAR; WAIT_L(0); MMA(1, 0, At, B0); BAR; SCHED;
;     LDB(B0, 1, 0); STAGE(SB(0, 1), Bt, bcol + HALF, t + 2);
;     BAR; MMA(1, 1, At, B1); BAR;
;     LDA(At, 1, 0); STAGE(SA(0, 1), A, brow + HALF, t + 2);
;     WAIT_L(8); BAR; WAIT_L(0); MMA(0, 0, At, B0); BAR; SCHED;
.LBB0_308:
	s_add_i32 s38, s1, s99
	s_add_i32 s6, s38, 0x80
	s_mov_b32 m0, s23
	ds_read_b128 v[170:173], v163
	ds_read_b128 v[174:177], v163 offset:1024
	ds_read_b128 v[178:181], v164
	ds_read_b128 v[182:185], v164 offset:1024
	ds_read_b128 v[186:189], v165
	ds_read_b128 v[190:193], v165 offset:1024
	ds_read_b128 v[194:197], v166
	ds_read_b128 v[204:207], v166 offset:1024
	buffer_load_dwordx4 v148, s[8:11], s6 offen lds
	s_mov_b32 m0, s22
	s_nop 0
	buffer_load_dwordx4 v149, s[8:11], s6 offen lds
	s_mul_i32 s6, s49, s15
	s_add_i32 s58, s6, s99
	s_mov_b32 m0, s88
	s_add_i32 vcc_hi, s58, 0x100
	s_mov_b32 s6, s10
	s_mov_b32 s7, s11
	ds_read_b128 v[208:211], v167
	ds_read_b128 v[212:215], v167 offset:1024
	ds_read_b128 v[216:219], v167 offset:2048
	ds_read_b128 v[220:223], v167 offset:3072
	buffer_load_dwordx4 v148, s[4:7], vcc_hi offen lds
	s_mov_b32 m0, s89
	s_add_i32 vcc_lo, vcc_lo, 2
	buffer_load_dwordx4 v149, s[4:7], vcc_hi offen lds
	s_waitcnt vmcnt(8) lgkmcnt(0)
	s_barrier
	s_setprio 1
	v_mfma_f32_16x16x32_bf16 v[138:141], v[170:173], v[2:5], v[138:141]
	v_mfma_f32_16x16x32_bf16 v[142:145], v[170:173], v[10:13], v[142:145]
	v_mfma_f32_16x16x32_bf16 v[134:137], v[178:181], v[2:5], v[134:137]
	v_mfma_f32_16x16x32_bf16 v[130:133], v[178:181], v[10:13], v[130:133]
	v_mfma_f32_16x16x32_bf16 v[126:129], v[186:189], v[2:5], v[126:129]
	v_mfma_f32_16x16x32_bf16 v[122:125], v[186:189], v[10:13], v[122:125]
	v_mfma_f32_16x16x32_bf16 v[118:121], v[194:197], v[2:5], v[118:121]
	v_mfma_f32_16x16x32_bf16 v[114:117], v[194:197], v[10:13], v[114:117]
	v_mfma_f32_16x16x32_bf16 v[138:141], v[174:177], v[6:9], v[138:141]
	v_mfma_f32_16x16x32_bf16 v[142:145], v[174:177], v[14:17], v[142:145]
	v_mfma_f32_16x16x32_bf16 v[134:137], v[182:185], v[6:9], v[134:137]
	v_mfma_f32_16x16x32_bf16 v[130:133], v[182:185], v[14:17], v[130:133]
	v_mfma_f32_16x16x32_bf16 v[126:129], v[190:193], v[6:9], v[126:129]
	v_mfma_f32_16x16x32_bf16 v[122:125], v[190:193], v[14:17], v[122:125]
	v_mfma_f32_16x16x32_bf16 v[118:121], v[204:207], v[6:9], v[118:121]
	v_mfma_f32_16x16x32_bf16 v[114:117], v[204:207], v[14:17], v[114:117]
	v_mfma_f32_16x16x32_bf16 v[110:113], v[170:173], v[208:211], v[110:113]
	v_mfma_f32_16x16x32_bf16 v[106:109], v[170:173], v[216:219], v[106:109]
	v_mfma_f32_16x16x32_bf16 v[102:105], v[178:181], v[208:211], v[102:105]
	v_mfma_f32_16x16x32_bf16 v[98:101], v[178:181], v[216:219], v[98:101]
	v_mfma_f32_16x16x32_bf16 v[94:97], v[186:189], v[208:211], v[94:97]
	v_mfma_f32_16x16x32_bf16 v[90:93], v[186:189], v[216:219], v[90:93]
	v_mfma_f32_16x16x32_bf16 v[86:89], v[194:197], v[208:211], v[86:89]
	v_mfma_f32_16x16x32_bf16 v[82:85], v[194:197], v[216:219], v[82:85]
	v_mfma_f32_16x16x32_bf16 v[110:113], v[174:177], v[212:215], v[110:113]
	v_mfma_f32_16x16x32_bf16 v[106:109], v[174:177], v[220:223], v[106:109]
	v_mfma_f32_16x16x32_bf16 v[102:105], v[182:185], v[212:215], v[102:105]
	v_mfma_f32_16x16x32_bf16 v[98:101], v[182:185], v[220:223], v[98:101]
	v_mfma_f32_16x16x32_bf16 v[94:97], v[190:193], v[212:215], v[94:97]
	v_mfma_f32_16x16x32_bf16 v[90:93], v[190:193], v[220:223], v[90:93]
	v_mfma_f32_16x16x32_bf16 v[86:89], v[204:207], v[212:215], v[86:89]
	v_mfma_f32_16x16x32_bf16 v[82:85], v[204:207], v[220:223], v[82:85]
	s_setprio 0
	s_mul_i32 vcc_hi, s49, s86
	s_add_i32 s40, vcc_hi, s99
	s_add_i32 vcc_hi, s40, 0x100
	s_mov_b32 m0, s52
	s_barrier
	ds_read_b128 v[170:173], v163 offset:16384
	ds_read_b128 v[174:177], v163 offset:17408
	ds_read_b128 v[178:181], v164 offset:16384
	ds_read_b128 v[182:185], v164 offset:17408
	ds_read_b128 v[186:189], v165 offset:16384
	ds_read_b128 v[190:193], v165 offset:17408
	ds_read_b128 v[194:197], v166 offset:16384
	ds_read_b128 v[204:207], v166 offset:17408
	buffer_load_dwordx4 v148, s[8:11], vcc_hi offen lds
	s_mov_b32 m0, s94
	s_nop 0
	buffer_load_dwordx4 v149, s[8:11], vcc_hi offen lds
	s_add_i32 s33, s98, s99
	s_add_i32 vcc_hi, s33, 0x100
	s_mov_b32 m0, s95
	ds_read_b128 v[232:235], v168
	ds_read_b128 v[236:239], v168 offset:1024
	ds_read_b128 v[240:243], v168 offset:2048
	ds_read_b128 v[244:247], v168 offset:3072
	buffer_load_dwordx4 v148, s[4:7], vcc_hi offen lds
	s_mov_b32 m0, s3
	s_nop 0
	buffer_load_dwordx4 v149, s[4:7], vcc_hi offen lds
	s_waitcnt vmcnt(8) lgkmcnt(0)
	s_barrier
	s_setprio 1
	v_mfma_f32_16x16x32_bf16 v[78:81], v[170:173], v[2:5], v[78:81]
	v_mfma_f32_16x16x32_bf16 v[70:73], v[178:181], v[2:5], v[70:73]
	v_mfma_f32_16x16x32_bf16 v[62:65], v[186:189], v[2:5], v[62:65]
	v_mfma_f32_16x16x32_bf16 v[248:251], v[194:197], v[2:5], v[54:57]
	v_mfma_f32_16x16x32_bf16 v[78:81], v[174:177], v[6:9], v[78:81]
	v_mfma_f32_16x16x32_bf16 v[74:77], v[170:173], v[10:13], v[74:77]
	v_mfma_f32_16x16x32_bf16 v[70:73], v[182:185], v[6:9], v[70:73]
	v_mfma_f32_16x16x32_bf16 v[66:69], v[178:181], v[10:13], v[66:69]
	v_mfma_f32_16x16x32_bf16 v[62:65], v[190:193], v[6:9], v[62:65]
	v_mfma_f32_16x16x32_bf16 v[58:61], v[186:189], v[10:13], v[58:61]
	v_mfma_f32_16x16x32_bf16 v[248:251], v[204:207], v[6:9], v[248:251]
	v_mfma_f32_16x16x32_bf16 v[252:255], v[194:197], v[10:13], v[50:53]
	v_mfma_f32_16x16x32_bf16 v[74:77], v[174:177], v[14:17], v[74:77]
	v_mfma_f32_16x16x32_bf16 v[66:69], v[182:185], v[14:17], v[66:69]
	v_mfma_f32_16x16x32_bf16 v[58:61], v[190:193], v[14:17], v[58:61]
	v_mfma_f32_16x16x32_bf16 v[252:255], v[204:207], v[14:17], v[252:255]
	v_mfma_f32_16x16x32_bf16 v[46:49], v[170:173], v[208:211], v[46:49]
	v_mfma_f32_16x16x32_bf16 v[42:45], v[170:173], v[216:219], v[42:45]
	v_mfma_f32_16x16x32_bf16 v[38:41], v[178:181], v[208:211], v[38:41]
	v_mfma_f32_16x16x32_bf16 v[34:37], v[178:181], v[216:219], v[34:37]
	v_mfma_f32_16x16x32_bf16 v[30:33], v[186:189], v[208:211], v[30:33]
	v_mfma_f32_16x16x32_bf16 v[26:29], v[186:189], v[216:219], v[26:29]
	v_mfma_f32_16x16x32_bf16 v[22:25], v[194:197], v[208:211], v[22:25]
	v_mfma_f32_16x16x32_bf16 v[18:21], v[194:197], v[216:219], v[18:21]
	v_mfma_f32_16x16x32_bf16 v[46:49], v[174:177], v[212:215], v[46:49]
	v_mfma_f32_16x16x32_bf16 v[42:45], v[174:177], v[220:223], v[42:45]
	v_mfma_f32_16x16x32_bf16 v[38:41], v[182:185], v[212:215], v[38:41]
	v_mfma_f32_16x16x32_bf16 v[34:37], v[182:185], v[220:223], v[34:37]
	v_mfma_f32_16x16x32_bf16 v[30:33], v[190:193], v[212:215], v[30:33]
	v_mfma_f32_16x16x32_bf16 v[26:29], v[190:193], v[220:223], v[26:29]
	v_mfma_f32_16x16x32_bf16 v[22:25], v[204:207], v[212:215], v[22:25]
	v_mfma_f32_16x16x32_bf16 v[18:21], v[204:207], v[220:223], v[18:21]
	s_setprio 0
	s_addk_i32 s38, 0x100
	s_mov_b32 m0, s57
	s_barrier
; #define STAGE(PP, RSRC, br, kt) do { const int _so = ((br) * K + (kt) * BK) * 2; \
;       __builtin_amdgcn_raw_ptr_buffer_load_lds(RSRC, LDSP((char*)(PP) + ldsoff), 16, voff0, _so, 0, 0); \
;       __builtin_amdgcn_raw_ptr_buffer_load_lds(RSRC, LDSP((char*)(PP) + ldsoff + 8192), 16, voff1, _so, 0, 0); \
;     } while (0)
; #define LDA(dst, b, h) for (int m = 0; m < 4; ++m) for (int k = 0; k < 2; ++k) \
;     dst[m][k] = *reinterpret_cast<const bf16x8*>((char*)SA(b, h) + lds_byte(wr * 64 + m * 16 + fr, k * 32 + fq * 8))
; #define LDB(dst, b, h) for (int n = 0; n < 2; ++n) for (int k = 0; k < 2; ++k) \
;     dst[n][k] = *reinterpret_cast<const bf16x8*>((char*)SB(b, h) + lds_byte(wc * 32 + n * 16 + fr, k * 32 + fq * 8))
; #define MMA(ai, bj, At_, Bt_) do { __builtin_amdgcn_s_setprio(1); \
;     for (int m = 0; m < 4; ++m) for (int n = 0; n < 2; ++n) for (int k = 0; k < 2; ++k) \
;       acc[ai][bj][m][n] = __builtin_amdgcn_mfma_f32_16x16x32_bf16(At_[m][k], Bt_[n][k], acc[ai][bj][m][n], 0, 0, 0); \
;     __builtin_amdgcn_s_setprio(0); } while (0)
; #define WAIT_V(n) asm volatile("s_waitcnt vmcnt(" #n ")" ::: "memory")
; #define WAIT_L(n) asm volatile("s_waitcnt lgkmcnt(" #n ")" ::: "memory")
; #define BAR __builtin_amdgcn_s_barrier()
; #define SCHED __builtin_amdgcn_sched_barrier(0)
; __device__ __forceinline__ void gemm_tile(const Params& P, const GArgs& ga, const TileDesc& td, int wid_s) {
;     ...
;     LDA(At, 1, 0); STAGE(SA(0, 1), A, brow + HALF, t + 2);
;     WAIT_L(8); BAR; WAIT_L(0); MMA(0, 0, At, B0); BAR; SCHED;
;     LDB(B1, 1, 1); STAGE(SB(1, 0), Bt, bcol, t + 3);
;     BAR; WAIT_L(0); MMA(0, 1, At, B1); BAR;
;     LDA(At, 1, 1); STAGE(SA(1, 0), A, brow, t + 3);
;     WAIT_V(4); BAR; WAIT_L(0); MMA(1, 0, At, B0); BAR; SCHED;
;     LDB(B0, 0, 0); STAGE(SB(1, 1), Bt, bcol + HALF, t + 3);
;     BAR; MMA(1, 1, At, B1); BAR;
;   }
	ds_read_b128 v[54:57], v163 offset:32768
	ds_read_b128 v[170:173], v163 offset:33792
	ds_read_b128 v[174:177], v164 offset:32768
	ds_read_b128 v[178:181], v164 offset:33792
	ds_read_b128 v[182:185], v165 offset:32768
	ds_read_b128 v[186:189], v165 offset:33792
	ds_read_b128 v[190:193], v166 offset:32768
	ds_read_b128 v[194:197], v166 offset:33792
	buffer_load_dwordx4 v148, s[8:11], s38 offen lds
	s_mov_b32 m0, s56
	s_nop 0
	buffer_load_dwordx4 v149, s[8:11], s38 offen lds
	s_addk_i32 s58, 0x180
	s_mov_b32 m0, s75
	ds_read_b128 v[204:207], v169
	ds_read_b128 v[208:211], v169 offset:1024
	ds_read_b128 v[212:215], v169 offset:2048
	ds_read_b128 v[216:219], v169 offset:3072
	buffer_load_dwordx4 v148, s[4:7], s58 offen lds
	s_mov_b32 m0, s74
	s_nop 0
	buffer_load_dwordx4 v149, s[4:7], s58 offen lds
	s_waitcnt vmcnt(8) lgkmcnt(0)
	s_barrier
	s_setprio 1
	v_mfma_f32_16x16x32_bf16 v[138:141], v[54:57], v[232:235], v[138:141]
	v_mfma_f32_16x16x32_bf16 v[142:145], v[54:57], v[240:243], v[142:145]
	v_mfma_f32_16x16x32_bf16 v[134:137], v[174:177], v[232:235], v[134:137]
	v_mfma_f32_16x16x32_bf16 v[130:133], v[174:177], v[240:243], v[130:133]
	v_mfma_f32_16x16x32_bf16 v[126:129], v[182:185], v[232:235], v[126:129]
	v_mfma_f32_16x16x32_bf16 v[122:125], v[182:185], v[240:243], v[122:125]
	v_mfma_f32_16x16x32_bf16 v[118:121], v[190:193], v[232:235], v[118:121]
	v_mfma_f32_16x16x32_bf16 v[114:117], v[190:193], v[240:243], v[114:117]
	v_mfma_f32_16x16x32_bf16 v[138:141], v[170:173], v[236:239], v[138:141]
	v_mfma_f32_16x16x32_bf16 v[142:145], v[170:173], v[244:247], v[142:145]
	v_mfma_f32_16x16x32_bf16 v[134:137], v[178:181], v[236:239], v[134:137]
	v_mfma_f32_16x16x32_bf16 v[130:133], v[178:181], v[244:247], v[130:133]
	v_mfma_f32_16x16x32_bf16 v[126:129], v[186:189], v[236:239], v[126:129]
	v_mfma_f32_16x16x32_bf16 v[122:125], v[186:189], v[244:247], v[122:125]
	v_mfma_f32_16x16x32_bf16 v[118:121], v[194:197], v[236:239], v[118:121]
	v_mfma_f32_16x16x32_bf16 v[114:117], v[194:197], v[244:247], v[114:117]
	v_mfma_f32_16x16x32_bf16 v[110:113], v[54:57], v[204:207], v[110:113]
	v_mfma_f32_16x16x32_bf16 v[54:57], v[54:57], v[212:215], v[106:109]
	v_mfma_f32_16x16x32_bf16 v[106:109], v[170:173], v[216:219], v[54:57]
	v_mfma_f32_16x16x32_bf16 v[54:57], v[174:177], v[204:207], v[102:105]
	v_mfma_f32_16x16x32_bf16 v[102:105], v[178:181], v[208:211], v[54:57]
	v_mfma_f32_16x16x32_bf16 v[54:57], v[174:177], v[212:215], v[98:101]
	v_mfma_f32_16x16x32_bf16 v[98:101], v[178:181], v[216:219], v[54:57]
	v_mfma_f32_16x16x32_bf16 v[54:57], v[182:185], v[204:207], v[94:97]
	v_mfma_f32_16x16x32_bf16 v[94:97], v[186:189], v[208:211], v[54:57]
	v_mfma_f32_16x16x32_bf16 v[54:57], v[182:185], v[212:215], v[90:93]
	v_mfma_f32_16x16x32_bf16 v[90:93], v[186:189], v[216:219], v[54:57]
	v_mfma_f32_16x16x32_bf16 v[54:57], v[190:193], v[204:207], v[86:89]
	v_mfma_f32_16x16x32_bf16 v[86:89], v[194:197], v[208:211], v[54:57]
	v_mfma_f32_16x16x32_bf16 v[54:57], v[190:193], v[212:215], v[82:85]
	v_mfma_f32_16x16x32_bf16 v[110:113], v[170:173], v[208:211], v[110:113]
	v_mfma_f32_16x16x32_bf16 v[82:85], v[194:197], v[216:219], v[54:57]
	s_setprio 0
	s_addk_i32 s40, 0x180
	s_mov_b32 m0, s83
	s_barrier
	ds_read_b128 v[170:173], v163 offset:49152
	ds_read_b128 v[174:177], v163 offset:50176
	ds_read_b128 v[178:181], v164 offset:49152
	ds_read_b128 v[182:185], v164 offset:50176
	ds_read_b128 v[186:189], v165 offset:49152
	ds_read_b128 v[190:193], v165 offset:50176
	ds_read_b128 v[194:197], v166 offset:49152
	ds_read_b128 v[220:223], v166 offset:50176
	buffer_load_dwordx4 v148, s[8:11], s40 offen lds
	s_mov_b32 m0, s82
	s_nop 0
	buffer_load_dwordx4 v149, s[8:11], s40 offen lds
	s_mov_b32 m0, s69
	s_addk_i32 s33, 0x180
	buffer_load_dwordx4 v148, s[4:7], s33 offen lds
	s_mov_b32 m0, s68
	s_nop 0
	buffer_load_dwordx4 v149, s[4:7], s33 offen lds
	ds_read_b128 v[2:5], v162
	ds_read_b128 v[6:9], v162 offset:1024
	ds_read_b128 v[10:13], v162 offset:2048
	ds_read_b128 v[14:17], v162 offset:3072
	s_waitcnt vmcnt(8) lgkmcnt(0)
	s_barrier
	s_setprio 1
	v_mfma_f32_16x16x32_bf16 v[54:57], v[170:173], v[232:235], v[78:81]
	v_mfma_f32_16x16x32_bf16 v[78:81], v[174:177], v[236:239], v[54:57]
	v_mfma_f32_16x16x32_bf16 v[54:57], v[170:173], v[240:243], v[74:77]
	v_mfma_f32_16x16x32_bf16 v[74:77], v[174:177], v[244:247], v[54:57]
	v_mfma_f32_16x16x32_bf16 v[54:57], v[178:181], v[232:235], v[70:73]
	v_mfma_f32_16x16x32_bf16 v[70:73], v[182:185], v[236:239], v[54:57]
	v_mfma_f32_16x16x32_bf16 v[54:57], v[178:181], v[240:243], v[66:69]
	v_mfma_f32_16x16x32_bf16 v[66:69], v[182:185], v[244:247], v[54:57]
	v_mfma_f32_16x16x32_bf16 v[54:57], v[186:189], v[232:235], v[62:65]
	v_mfma_f32_16x16x32_bf16 v[62:65], v[190:193], v[236:239], v[54:57]
	v_mfma_f32_16x16x32_bf16 v[54:57], v[186:189], v[240:243], v[58:61]
	v_mfma_f32_16x16x32_bf16 v[248:251], v[194:197], v[232:235], v[248:251]
	v_mfma_f32_16x16x32_bf16 v[58:61], v[190:193], v[244:247], v[54:57]
	v_mfma_f32_16x16x32_bf16 v[54:57], v[220:223], v[236:239], v[248:251]
	v_mfma_f32_16x16x32_bf16 v[248:251], v[194:197], v[240:243], v[252:255]
	v_mfma_f32_16x16x32_bf16 v[50:53], v[220:223], v[244:247], v[248:251]
	v_mfma_f32_16x16x32_bf16 v[46:49], v[170:173], v[204:207], v[46:49]
	v_mfma_f32_16x16x32_bf16 v[42:45], v[170:173], v[212:215], v[42:45]
	v_mfma_f32_16x16x32_bf16 v[38:41], v[178:181], v[204:207], v[38:41]
	v_mfma_f32_16x16x32_bf16 v[34:37], v[178:181], v[212:215], v[34:37]
	v_mfma_f32_16x16x32_bf16 v[30:33], v[186:189], v[204:207], v[30:33]
	v_mfma_f32_16x16x32_bf16 v[26:29], v[186:189], v[212:215], v[26:29]
	v_mfma_f32_16x16x32_bf16 v[22:25], v[194:197], v[204:207], v[22:25]
	v_mfma_f32_16x16x32_bf16 v[18:21], v[194:197], v[212:215], v[18:21]
	v_mfma_f32_16x16x32_bf16 v[46:49], v[174:177], v[208:211], v[46:49]
	v_mfma_f32_16x16x32_bf16 v[42:45], v[174:177], v[216:219], v[42:45]
	v_mfma_f32_16x16x32_bf16 v[38:41], v[182:185], v[208:211], v[38:41]
	v_mfma_f32_16x16x32_bf16 v[34:37], v[182:185], v[216:219], v[34:37]
	v_mfma_f32_16x16x32_bf16 v[30:33], v[190:193], v[208:211], v[30:33]
	v_mfma_f32_16x16x32_bf16 v[26:29], v[190:193], v[216:219], v[26:29]
	v_mfma_f32_16x16x32_bf16 v[22:25], v[220:223], v[208:211], v[22:25]
	v_mfma_f32_16x16x32_bf16 v[18:21], v[220:223], v[216:219], v[18:21]
	s_setprio 0
	s_addk_i32 s99, 0x100
	s_cmp_lt_i32 vcc_lo, s0
	s_barrier
	s_cbranch_scc1 .LBB0_308
	s_mov_b64 s[98:99], s[50:51]
	s_mov_b32 s58, s90
	s_branch .LBB0_311

; #define STAGE(PP, RSRC, br, kt) do { const int _so = ((br) * K + (kt) * BK) * 2; \
;       __builtin_amdgcn_raw_ptr_buffer_load_lds(RSRC, LDSP((char*)(PP) + ldsoff), 16, voff0, _so, 0, 0); \
;       __builtin_amdgcn_raw_ptr_buffer_load_lds(RSRC, LDSP((char*)(PP) + ldsoff + 8192), 16, voff1, _so, 0, 0); \
;     } while (0)
; #define LDA(dst, b, h) for (int m = 0; m < 4; ++m) for (int k = 0; k < 2; ++k) \
;     dst[m][k] = *reinterpret_cast<const bf16x8*>((char*)SA(b, h) + lds_byte(wr * 64 + m * 16 + fr, k * 32 + fq * 8))
; #define LDB(dst, b, h) for (int n = 0; n < 2; ++n) for (int k = 0; k < 2; ++k) \
;     dst[n][k] = *reinterpret_cast<const bf16x8*>((char*)SB(b, h) + lds_byte(wc * 32 + n * 16 + fr, k * 32 + fq * 8))
; #define MMA(ai, bj, At_, Bt_) do { __builtin_amdgcn_s_setprio(1); \
;     for (int m = 0; m < 4; ++m) for (int n = 0; n < 2; ++n) for (int k = 0; k < 2; ++k) \
;       acc[ai][bj][m][n] = __builtin_amdgcn_mfma_f32_16x16x32_bf16(At_[m][k], Bt_[n][k], acc[ai][bj][m][n], 0, 0, 0); \
;     __builtin_amdgcn_s_setprio(0); } while (0)
; #define WAIT_V(n) asm volatile("s_waitcnt vmcnt(" #n ")" ::: "memory")
; #define WAIT_L(n) asm volatile("s_waitcnt lgkmcnt(" #n ")" ::: "memory")
; #define BAR __builtin_amdgcn_s_barrier()
; __device__ __forceinline__ void gemm_tile(const Params& P, const GArgs& ga, const TileDesc& td, int wid_s) {
;     ...
;   { LDA(At, 0, 0); STAGE(SA(1, 1), A, brow + HALF, nt - 1);
;     BAR; WAIT_L(0); MMA(0, 0, At, B0); BAR;
;     LDB(B1, 0, 1); BAR; WAIT_L(0); MMA(0, 1, At, B1); BAR;
;     LDA(At, 0, 1); WAIT_V(4); BAR; WAIT_L(0); MMA(1, 0, At, B0); MMA(1, 1, At, B1); BAR; }
;   { LDB(B0, 1, 0); LDA(At, 1, 0); WAIT_V(2); BAR; WAIT_L(0); MMA(0, 0, At, B0); BAR;
;     LDB(B1, 1, 1); WAIT_V(0); BAR; WAIT_L(0); MMA(0, 1, At, B1); BAR;
.LBB0_311:
	v_add_u32_e32 v150, 0, v150
	v_add_u32_e32 v154, 0, v154
	s_lshl_b32 s0, s17, 7
	v_add_u32_e32 v198, v150, v159
	v_add_u32_e32 v199, v150, v151
	v_add_u32_e32 v150, 0, v152
	v_add_u32_e32 v225, v154, v160
	v_add_u32_e32 v226, v154, v155
	v_add_u32_e32 v154, 0, v156
	s_add_i32 s0, s85, s0
	v_add_u32_e32 v203, v150, v161
	v_add_u32_e32 v227, v154, v158
	s_addk_i32 s0, 0xff80
	s_mov_b32 m0, s23
	ds_read_b128 v[162:165], v198
	ds_read_b128 v[166:169], v199
	v_add_u32_e32 v224, v150, v153
	ds_read_b128 v[150:153], v203
	ds_read_b128 v[170:173], v224
	ds_read_b128 v[174:177], v225
	ds_read_b128 v[178:181], v226
	v_add_u32_e32 v228, v154, v157
	ds_read_b128 v[154:157], v227
	ds_read_b128 v[158:161], v228
	buffer_load_dwordx4 v148, s[8:11], s0 offen lds
	s_mov_b32 m0, s22
	s_nop 0
	buffer_load_dwordx4 v149, s[8:11], s0 offen lds
	s_waitcnt vmcnt(10)
	s_barrier
	s_waitcnt lgkmcnt(0)
	s_setprio 1
	s_waitcnt lgkmcnt(3)
	v_mfma_f32_16x16x32_bf16 v[126:129], v[174:177], v[2:5], v[126:129]
	v_mfma_f32_16x16x32_bf16 v[122:125], v[174:177], v[10:13], v[122:125]
	v_mfma_f32_16x16x32_bf16 v[138:141], v[162:165], v[2:5], v[138:141]
	v_mfma_f32_16x16x32_bf16 v[142:145], v[162:165], v[10:13], v[142:145]
	v_mfma_f32_16x16x32_bf16 v[134:137], v[150:153], v[2:5], v[134:137]
	v_mfma_f32_16x16x32_bf16 v[130:133], v[150:153], v[10:13], v[130:133]
	s_waitcnt lgkmcnt(2)
	v_mfma_f32_16x16x32_bf16 v[126:129], v[178:181], v[6:9], v[126:129]
	v_mfma_f32_16x16x32_bf16 v[122:125], v[178:181], v[14:17], v[122:125]
	s_waitcnt lgkmcnt(1)
	v_mfma_f32_16x16x32_bf16 v[118:121], v[154:157], v[2:5], v[118:121]
	v_mfma_f32_16x16x32_bf16 v[114:117], v[154:157], v[10:13], v[114:117]
	v_mfma_f32_16x16x32_bf16 v[138:141], v[166:169], v[6:9], v[138:141]
	v_mfma_f32_16x16x32_bf16 v[142:145], v[166:169], v[14:17], v[142:145]
	v_mfma_f32_16x16x32_bf16 v[134:137], v[170:173], v[6:9], v[134:137]
	v_mfma_f32_16x16x32_bf16 v[130:133], v[170:173], v[14:17], v[130:133]
	s_waitcnt lgkmcnt(0)
	v_mfma_f32_16x16x32_bf16 v[182:185], v[158:161], v[6:9], v[118:121]
	v_mfma_f32_16x16x32_bf16 v[186:189], v[158:161], v[14:17], v[114:117]
	s_setprio 0
	s_add_i32 s0, 0, 0x14000
	v_add3_u32 v148, s0, v146, v147
	s_barrier
	ds_read_b128 v[114:117], v148
	ds_read_b128 v[118:121], v148 offset:1024
	ds_read_b128 v[190:193], v148 offset:2048
	ds_read_b128 v[194:197], v148 offset:3072
	s_waitcnt vmcnt(8)
	s_barrier
	s_waitcnt lgkmcnt(0)
	s_setprio 1
	s_waitcnt lgkmcnt(3)
	v_mfma_f32_16x16x32_bf16 v[110:113], v[162:165], v[114:117], v[110:113]
	s_waitcnt lgkmcnt(1)
	v_mfma_f32_16x16x32_bf16 v[106:109], v[162:165], v[190:193], v[106:109]
	v_mfma_f32_16x16x32_bf16 v[94:97], v[174:177], v[114:117], v[94:97]
	v_mfma_f32_16x16x32_bf16 v[90:93], v[174:177], v[190:193], v[90:93]
	v_mfma_f32_16x16x32_bf16 v[110:113], v[166:169], v[118:121], v[110:113]
	s_waitcnt lgkmcnt(0)
	v_mfma_f32_16x16x32_bf16 v[106:109], v[166:169], v[194:197], v[106:109]
	v_mfma_f32_16x16x32_bf16 v[102:105], v[150:153], v[114:117], v[102:105]
	v_mfma_f32_16x16x32_bf16 v[98:101], v[150:153], v[190:193], v[98:101]
	v_mfma_f32_16x16x32_bf16 v[94:97], v[178:181], v[118:121], v[94:97]
	v_mfma_f32_16x16x32_bf16 v[90:93], v[178:181], v[194:197], v[90:93]
	v_mfma_f32_16x16x32_bf16 v[86:89], v[154:157], v[114:117], v[86:89]
	v_mfma_f32_16x16x32_bf16 v[82:85], v[154:157], v[190:193], v[82:85]
	v_mfma_f32_16x16x32_bf16 v[162:165], v[170:173], v[118:121], v[102:105]
	v_mfma_f32_16x16x32_bf16 v[148:151], v[170:173], v[194:197], v[98:101]
	v_mfma_f32_16x16x32_bf16 v[166:169], v[158:161], v[118:121], v[86:89]
	v_mfma_f32_16x16x32_bf16 v[152:155], v[158:161], v[194:197], v[82:85]
	s_setprio 0
	s_barrier
	s_nop 1
	ds_read_b128 v[82:85], v198 offset:16384
	ds_read_b128 v[86:89], v199 offset:16384
	ds_read_b128 v[98:101], v203 offset:16384
	ds_read_b128 v[102:105], v224 offset:16384
	ds_read_b128 v[156:159], v225 offset:16384
	ds_read_b128 v[170:173], v226 offset:16384
	ds_read_b128 v[174:177], v227 offset:16384
	ds_read_b128 v[178:181], v228 offset:16384
	s_waitcnt vmcnt(4)
	s_barrier
	s_waitcnt lgkmcnt(0)
	s_setprio 1
	s_waitcnt lgkmcnt(7)
	v_mfma_f32_16x16x32_bf16 v[78:81], v[82:85], v[2:5], v[78:81]
	s_waitcnt lgkmcnt(5)
	v_mfma_f32_16x16x32_bf16 v[70:73], v[98:101], v[2:5], v[70:73]
	s_waitcnt lgkmcnt(3)
	v_mfma_f32_16x16x32_bf16 v[62:65], v[156:159], v[2:5], v[62:65]
	s_waitcnt lgkmcnt(1)
	v_mfma_f32_16x16x32_bf16 v[2:5], v[174:177], v[2:5], v[54:57]
	v_mfma_f32_16x16x32_bf16 v[204:207], v[86:89], v[6:9], v[78:81]
	v_mfma_f32_16x16x32_bf16 v[212:215], v[102:105], v[6:9], v[70:73]
	v_mfma_f32_16x16x32_bf16 v[62:65], v[170:173], v[6:9], v[62:65]
	v_mfma_f32_16x16x32_bf16 v[58:61], v[156:159], v[10:13], v[58:61]
	s_waitcnt lgkmcnt(0)
	v_mfma_f32_16x16x32_bf16 v[2:5], v[178:181], v[6:9], v[2:5]
	v_mfma_f32_16x16x32_bf16 v[6:9], v[174:177], v[10:13], v[50:53]
	v_mfma_f32_16x16x32_bf16 v[74:77], v[82:85], v[10:13], v[74:77]
	v_mfma_f32_16x16x32_bf16 v[66:69], v[98:101], v[10:13], v[66:69]
	v_mfma_f32_16x16x32_bf16 v[58:61], v[170:173], v[14:17], v[58:61]
	v_mfma_f32_16x16x32_bf16 v[6:9], v[178:181], v[14:17], v[6:9]
	v_mfma_f32_16x16x32_bf16 v[208:211], v[86:89], v[14:17], v[74:77]
	v_mfma_f32_16x16x32_bf16 v[216:219], v[102:105], v[14:17], v[66:69]
	s_setprio 0
	s_setprio 1
	v_mfma_f32_16x16x32_bf16 v[10:13], v[82:85], v[114:117], v[46:49]
	v_mfma_f32_16x16x32_bf16 v[14:17], v[82:85], v[190:193], v[42:45]
	v_mfma_f32_16x16x32_bf16 v[38:41], v[98:101], v[114:117], v[38:41]
	v_mfma_f32_16x16x32_bf16 v[30:33], v[156:159], v[114:117], v[30:33]
	v_mfma_f32_16x16x32_bf16 v[26:29], v[156:159], v[190:193], v[26:29]
	v_mfma_f32_16x16x32_bf16 v[10:13], v[86:89], v[118:121], v[10:13]
	v_mfma_f32_16x16x32_bf16 v[14:17], v[86:89], v[194:197], v[14:17]
	v_mfma_f32_16x16x32_bf16 v[42:45], v[102:105], v[118:121], v[38:41]
	v_mfma_f32_16x16x32_bf16 v[34:37], v[98:101], v[190:193], v[34:37]
	v_mfma_f32_16x16x32_bf16 v[30:33], v[170:173], v[118:121], v[30:33]
	v_mfma_f32_16x16x32_bf16 v[26:29], v[170:173], v[194:197], v[26:29]
	v_mfma_f32_16x16x32_bf16 v[22:25], v[174:177], v[114:117], v[22:25]
	v_mfma_f32_16x16x32_bf16 v[18:21], v[174:177], v[190:193], v[18:21]
	v_mfma_f32_16x16x32_bf16 v[220:223], v[102:105], v[194:197], v[34:37]
	v_mfma_f32_16x16x32_bf16 v[156:159], v[178:181], v[118:121], v[22:25]
	v_mfma_f32_16x16x32_bf16 v[170:173], v[178:181], v[194:197], v[18:21]
	s_setprio 0
	s_add_i32 s0, 0, 0x18000
	s_nop 2
	v_add3_u32 v18, s0, v146, v147
	s_barrier
; #define LDA(dst, b, h) for (int m = 0; m < 4; ++m) for (int k = 0; k < 2; ++k) \
;     dst[m][k] = *reinterpret_cast<const bf16x8*>((char*)SA(b, h) + lds_byte(wr * 64 + m * 16 + fr, k * 32 + fq * 8))
; #define LDB(dst, b, h) for (int n = 0; n < 2; ++n) for (int k = 0; k < 2; ++k) \
;     dst[n][k] = *reinterpret_cast<const bf16x8*>((char*)SB(b, h) + lds_byte(wc * 32 + n * 16 + fr, k * 32 + fq * 8))
; #define MMA(ai, bj, At_, Bt_) do { __builtin_amdgcn_s_setprio(1); \
;     for (int m = 0; m < 4; ++m) for (int n = 0; n < 2; ++n) for (int k = 0; k < 2; ++k) \
;       acc[ai][bj][m][n] = __builtin_amdgcn_mfma_f32_16x16x32_bf16(At_[m][k], Bt_[n][k], acc[ai][bj][m][n], 0, 0, 0); \
;     __builtin_amdgcn_s_setprio(0); } while (0)
; #define WAIT_V(n) asm volatile("s_waitcnt vmcnt(" #n ")" ::: "memory")
; #define WAIT_L(n) asm volatile("s_waitcnt lgkmcnt(" #n ")" ::: "memory")
; #define BAR __builtin_amdgcn_s_barrier()
; __device__ __forceinline__ void gemm_tile(const Params& P, const GArgs& ga, const TileDesc& td, int wid_s) {
;     ...
;     LDA(At, 0, 1); WAIT_V(4); BAR; WAIT_L(0); MMA(1, 0, At, B0); MMA(1, 1, At, B1); BAR; }
;   { LDB(B0, 1, 0); LDA(At, 1, 0); WAIT_V(2); BAR; WAIT_L(0); MMA(0, 0, At, B0); BAR;
;     LDB(B1, 1, 1); WAIT_V(0); BAR; WAIT_L(0); MMA(0, 1, At, B1); BAR;
;     LDA(At, 1, 1); BAR; WAIT_L(0); MMA(1, 0, At, B0); MMA(1, 1, At, B1); BAR; }
;   if (wr == 0) BAR;
	ds_read_b128 v[46:49], v18
	ds_read_b128 v[174:177], v18 offset:1024
	ds_read_b128 v[178:181], v18 offset:2048
	ds_read_b128 v[190:193], v18 offset:3072
	ds_read_b128 v[18:21], v198 offset:32768
	ds_read_b128 v[22:25], v199 offset:32768
	ds_read_b128 v[34:37], v203 offset:32768
	ds_read_b128 v[38:41], v224 offset:32768
	ds_read_b128 v[50:53], v225 offset:32768
	ds_read_b128 v[54:57], v226 offset:32768
	ds_read_b128 v[74:77], v227 offset:32768
	ds_read_b128 v[194:197], v228 offset:32768
	s_waitcnt vmcnt(2)
	s_barrier
	s_waitcnt lgkmcnt(0)
	s_setprio 1
	s_waitcnt lgkmcnt(7)
	v_mfma_f32_16x16x32_bf16 v[66:69], v[18:21], v[46:49], v[138:141]
	s_waitcnt lgkmcnt(6)
	v_mfma_f32_16x16x32_bf16 v[114:117], v[22:25], v[174:177], v[66:69]
	v_mfma_f32_16x16x32_bf16 v[66:69], v[18:21], v[178:181], v[142:145]
	v_mfma_f32_16x16x32_bf16 v[118:121], v[22:25], v[190:193], v[66:69]
	s_waitcnt lgkmcnt(5)
	v_mfma_f32_16x16x32_bf16 v[66:69], v[34:37], v[46:49], v[134:137]
	s_waitcnt lgkmcnt(4)
	v_mfma_f32_16x16x32_bf16 v[98:101], v[38:41], v[174:177], v[66:69]
	v_mfma_f32_16x16x32_bf16 v[66:69], v[34:37], v[178:181], v[130:133]
	v_mfma_f32_16x16x32_bf16 v[102:105], v[38:41], v[190:193], v[66:69]
	s_waitcnt lgkmcnt(3)
	v_mfma_f32_16x16x32_bf16 v[66:69], v[50:53], v[46:49], v[126:129]
	s_waitcnt lgkmcnt(2)
	v_mfma_f32_16x16x32_bf16 v[82:85], v[54:57], v[174:177], v[66:69]
	v_mfma_f32_16x16x32_bf16 v[66:69], v[50:53], v[178:181], v[122:125]
	v_mfma_f32_16x16x32_bf16 v[86:89], v[54:57], v[190:193], v[66:69]
	s_waitcnt lgkmcnt(1)
	v_mfma_f32_16x16x32_bf16 v[66:69], v[74:77], v[46:49], v[182:185]
	v_mfma_f32_16x16x32_bf16 v[70:73], v[74:77], v[178:181], v[186:189]
	s_waitcnt lgkmcnt(0)
	v_mfma_f32_16x16x32_bf16 v[66:69], v[194:197], v[174:177], v[66:69]
	v_mfma_f32_16x16x32_bf16 v[70:73], v[194:197], v[190:193], v[70:73]
	s_setprio 0
	s_add_i32 s0, 0, 0x1c000
	v_add3_u32 v78, s0, v146, v147
	s_barrier
	ds_read_b128 v[130:133], v78
	ds_read_b128 v[134:137], v78 offset:1024
	ds_read_b128 v[138:141], v78 offset:2048
	ds_read_b128 v[142:145], v78 offset:3072
	s_waitcnt vmcnt(0)
	s_barrier
	s_waitcnt lgkmcnt(0)
	s_setprio 1
	s_waitcnt lgkmcnt(3)
	v_mfma_f32_16x16x32_bf16 v[78:81], v[18:21], v[130:133], v[110:113]
	s_waitcnt lgkmcnt(1)
	v_mfma_f32_16x16x32_bf16 v[18:21], v[18:21], v[138:141], v[106:109]
	s_waitcnt lgkmcnt(0)
	v_mfma_f32_16x16x32_bf16 v[122:125], v[22:25], v[142:145], v[18:21]
	v_mfma_f32_16x16x32_bf16 v[18:21], v[34:37], v[130:133], v[162:165]
	v_mfma_f32_16x16x32_bf16 v[110:113], v[38:41], v[134:137], v[18:21]
	v_mfma_f32_16x16x32_bf16 v[18:21], v[34:37], v[138:141], v[148:151]
	v_mfma_f32_16x16x32_bf16 v[106:109], v[38:41], v[142:145], v[18:21]
	v_mfma_f32_16x16x32_bf16 v[18:21], v[50:53], v[130:133], v[94:97]
	v_mfma_f32_16x16x32_bf16 v[94:97], v[54:57], v[134:137], v[18:21]
	v_mfma_f32_16x16x32_bf16 v[18:21], v[50:53], v[138:141], v[90:93]
	v_mfma_f32_16x16x32_bf16 v[90:93], v[54:57], v[142:145], v[18:21]
	v_mfma_f32_16x16x32_bf16 v[18:21], v[74:77], v[130:133], v[166:169]
	v_mfma_f32_16x16x32_bf16 v[126:129], v[22:25], v[134:137], v[78:81]
	v_mfma_f32_16x16x32_bf16 v[78:81], v[194:197], v[134:137], v[18:21]
	v_mfma_f32_16x16x32_bf16 v[18:21], v[74:77], v[138:141], v[152:155]
	v_mfma_f32_16x16x32_bf16 v[74:77], v[194:197], v[142:145], v[18:21]
	s_setprio 0
	s_barrier
	ds_read_b128 v[146:149], v198 offset:49152
	ds_read_b128 v[150:153], v199 offset:49152
	ds_read_b128 v[160:163], v203 offset:49152
	ds_read_b128 v[164:167], v224 offset:49152
	ds_read_b128 v[182:185], v225 offset:49152
	ds_read_b128 v[186:189], v226 offset:49152
	ds_read_b128 v[194:197], v227 offset:49152
	ds_read_b128 v[224:227], v228 offset:49152
	s_barrier
	s_waitcnt lgkmcnt(0)
	s_setprio 1
	s_waitcnt lgkmcnt(7)
	v_mfma_f32_16x16x32_bf16 v[18:21], v[146:149], v[46:49], v[204:207]
	s_waitcnt lgkmcnt(6)
	v_mfma_f32_16x16x32_bf16 v[50:53], v[150:153], v[174:177], v[18:21]
	v_mfma_f32_16x16x32_bf16 v[18:21], v[146:149], v[178:181], v[208:211]
	v_mfma_f32_16x16x32_bf16 v[54:57], v[150:153], v[190:193], v[18:21]
	s_waitcnt lgkmcnt(5)
	v_mfma_f32_16x16x32_bf16 v[18:21], v[160:163], v[46:49], v[212:215]
	s_waitcnt lgkmcnt(4)
	v_mfma_f32_16x16x32_bf16 v[34:37], v[164:167], v[174:177], v[18:21]
	v_mfma_f32_16x16x32_bf16 v[18:21], v[160:163], v[178:181], v[216:219]
	v_mfma_f32_16x16x32_bf16 v[38:41], v[164:167], v[190:193], v[18:21]
	s_waitcnt lgkmcnt(3)
	v_mfma_f32_16x16x32_bf16 v[18:21], v[182:185], v[46:49], v[62:65]
	v_mfma_f32_16x16x32_bf16 v[22:25], v[182:185], v[178:181], v[58:61]
	s_waitcnt lgkmcnt(1)
	v_mfma_f32_16x16x32_bf16 v[2:5], v[194:197], v[46:49], v[2:5]
	v_mfma_f32_16x16x32_bf16 v[6:9], v[194:197], v[178:181], v[6:9]
	v_mfma_f32_16x16x32_bf16 v[18:21], v[186:189], v[174:177], v[18:21]
	v_mfma_f32_16x16x32_bf16 v[22:25], v[186:189], v[190:193], v[22:25]
	s_waitcnt lgkmcnt(0)
	v_mfma_f32_16x16x32_bf16 v[2:5], v[224:227], v[174:177], v[2:5]
	v_mfma_f32_16x16x32_bf16 v[6:9], v[224:227], v[190:193], v[6:9]
	s_setprio 0
	s_setprio 1
	v_mfma_f32_16x16x32_bf16 v[10:13], v[146:149], v[130:133], v[10:13]
	v_mfma_f32_16x16x32_bf16 v[62:65], v[150:153], v[134:137], v[10:13]
	v_mfma_f32_16x16x32_bf16 v[10:13], v[146:149], v[138:141], v[14:17]
	v_mfma_f32_16x16x32_bf16 v[58:61], v[150:153], v[142:145], v[10:13]
	v_mfma_f32_16x16x32_bf16 v[10:13], v[160:163], v[130:133], v[42:45]
	v_mfma_f32_16x16x32_bf16 v[46:49], v[164:167], v[134:137], v[10:13]
	v_mfma_f32_16x16x32_bf16 v[10:13], v[160:163], v[138:141], v[220:223]
	v_mfma_f32_16x16x32_bf16 v[42:45], v[164:167], v[142:145], v[10:13]
	v_mfma_f32_16x16x32_bf16 v[10:13], v[182:185], v[130:133], v[30:33]
	v_mfma_f32_16x16x32_bf16 v[30:33], v[186:189], v[134:137], v[10:13]
	v_mfma_f32_16x16x32_bf16 v[10:13], v[182:185], v[138:141], v[26:29]
	v_mfma_f32_16x16x32_bf16 v[26:29], v[186:189], v[142:145], v[10:13]
	v_mfma_f32_16x16x32_bf16 v[10:13], v[194:197], v[130:133], v[156:159]
	v_mfma_f32_16x16x32_bf16 v[14:17], v[224:227], v[134:137], v[10:13]
	v_mfma_f32_16x16x32_bf16 v[10:13], v[194:197], v[138:141], v[170:173]
	v_mfma_f32_16x16x32_bf16 v[10:13], v[224:227], v[142:145], v[10:13]
	s_setprio 0
	s_movk_i32 s0, 0x100
	v_cmp_gt_u32_e32 vcc, s0, v0
	s_barrier
	s_and_saveexec_b64 s[0:1], vcc
	s_cbranch_execz .LBB0_313
	s_barrier

; __global__ void __launch_bounds__(512, 2) mega(Params P) {
;   extern __shared__ __attribute__((aligned(16))) u16 shm[];
;   const int wid_s = __builtin_amdgcn_readfirstlane((int)threadIdx.x >> 6);
	.amdhsa_kernel _Z4mega6Params
		.amdhsa_group_segment_fixed_size 0
		.amdhsa_private_segment_fixed_size 0
		.amdhsa_kernarg_size 464
		.amdhsa_user_sgpr_count 2
		.amdhsa_user_sgpr_dispatch_ptr 0
		.amdhsa_user_sgpr_queue_ptr 0
		.amdhsa_user_sgpr_kernarg_segment_ptr 1
		.amdhsa_user_sgpr_dispatch_id 0
		.amdhsa_user_sgpr_kernarg_preload_length 0
		.amdhsa_user_sgpr_kernarg_preload_offset 0
		.amdhsa_user_sgpr_private_segment_size 0
		.amdhsa_uses_dynamic_stack 0
		.amdhsa_enable_private_segment 0
		.amdhsa_system_sgpr_workgroup_id_x 1
		.amdhsa_system_sgpr_workgroup_id_y 0
		.amdhsa_system_sgpr_workgroup_id_z 0
		.amdhsa_system_sgpr_workgroup_info 0
		.amdhsa_system_vgpr_workitem_id 2
		.amdhsa_next_free_vgpr 256
		.amdhsa_next_free_sgpr 100
		.amdhsa_accum_offset 256
		.amdhsa_reserve_vcc 1
		.amdhsa_float_round_mode_32 0
		.amdhsa_float_round_mode_16_64 0
		.amdhsa_float_denorm_mode_32 3
		.amdhsa_float_denorm_mode_16_64 3
		.amdhsa_dx10_clamp 1
		.amdhsa_ieee_mode 1
		.amdhsa_fp16_overflow 0
		.amdhsa_tg_split 0
		.amdhsa_exception_fp_ieee_invalid_op 0
		.amdhsa_exception_fp_denorm_src 0
		.amdhsa_exception_fp_ieee_div_zero 0
		.amdhsa_exception_fp_ieee_overflow 0
		.amdhsa_exception_fp_ieee_underflow 0
		.amdhsa_exception_fp_ieee_inexact 0
		.amdhsa_exception_int_div_zero 0
	.end_amdhsa_kernel

; __global__ void __launch_bounds__(512, 2) mega(Params P) {
;   extern __shared__ __attribute__((aligned(16))) u16 shm[];
;   const int wid_s = __builtin_amdgcn_readfirstlane((int)threadIdx.x >> 6);
amdhsa.kernels:
  - .agpr_count:     0
    .args:
      - .offset:         0
        .size:           208
        .value_kind:     by_value
      - .offset:         208
        .size:           4
        .value_kind:     hidden_block_count_x
      - .offset:         212
        .size:           4
        .value_kind:     hidden_block_count_y
      - .offset:         216
        .size:           4
        .value_kind:     hidden_block_count_z
      - .offset:         220
        .size:           2
        .value_kind:     hidden_group_size_x
      - .offset:         222
        .size:           2
        .value_kind:     hidden_group_size_y
      - .offset:         224
        .size:           2
        .value_kind:     hidden_group_size_z
      - .offset:         226
        .size:           2
        .value_kind:     hidden_remainder_x
      - .offset:         228
        .size:           2
        .value_kind:     hidden_remainder_y
      - .offset:         230
        .size:           2
        .value_kind:     hidden_remainder_z
      - .offset:         248
        .size:           8
        .value_kind:     hidden_global_offset_x
      - .offset:         256
        .size:           8
        .value_kind:     hidden_global_offset_y
      - .offset:         264
        .size:           8
        .value_kind:     hidden_global_offset_z
      - .offset:         272
        .size:           2
        .value_kind:     hidden_grid_dims
      - .offset:         296
        .size:           8
        .value_kind:     hidden_multigrid_sync_arg
      - .offset:         328
        .size:           4
        .value_kind:     hidden_dynamic_lds_size
    .group_segment_fixed_size: 0
    .kernarg_segment_align: 8
    .kernarg_segment_size: 464
    .language:       OpenCL C
    .language_version:
      - 2
      - 0
    .max_flat_workgroup_size: 512
    .name:           _Z4mega6Params
    .private_segment_fixed_size: 0
    .sgpr_count:     106
    .sgpr_spill_count: 137
    .symbol:         _Z4mega6Params.kd
    .uniform_work_group_size: 1
    .uses_dynamic_stack: false
    .vgpr_count:     256
    .vgpr_spill_count: 0
    .wavefront_size: 64
